# R3 k/v stage: QK^T reads hand-scheduled four fragments ahead over four independent accumulators
# speedup vs baseline: 1.0044x; 1.0022x over previous
.LBB0_1097:
	s_bitcmp1_b32 s58, 0
	s_cselect_b32 s10, 0x11000, 0
	s_add_i32 s12, s10, 0
	v_add3_u32 v178, s12, v194, v212
	ds_read_b128 v[116:119], v178
	ds_read_b128 v[120:123], v178 offset:8704
	ds_read_b128 v[244:247], v178 offset:17408
	ds_read_b128 v[250:253], v178 offset:26112
	s_waitcnt lgkmcnt(3)
	v_mfma_f32_16x16x32_bf16 v[60:63], v[116:119], v[0:3], 0
	ds_read_b128 v[116:119], v178 offset:64
	s_waitcnt lgkmcnt(3)
	v_mfma_f32_16x16x32_bf16 v[104:107], v[120:123], v[0:3], 0
	ds_read_b128 v[120:123], v178 offset:8768
	s_waitcnt lgkmcnt(3)
	v_mfma_f32_16x16x32_bf16 v[108:111], v[244:247], v[0:3], 0
	ds_read_b128 v[244:247], v178 offset:17472
	s_waitcnt lgkmcnt(3)
	v_mfma_f32_16x16x32_bf16 v[56:59], v[250:253], v[0:3], 0
	ds_read_b128 v[250:253], v178 offset:26176
	s_waitcnt lgkmcnt(3)
	v_mfma_f32_16x16x32_bf16 v[60:63], v[116:119], v[4:7], v[60:63]
	ds_read_b128 v[116:119], v178 offset:128
	s_waitcnt lgkmcnt(3)
	v_mfma_f32_16x16x32_bf16 v[104:107], v[120:123], v[4:7], v[104:107]
	ds_read_b128 v[120:123], v178 offset:8832
	s_waitcnt lgkmcnt(3)
	v_mfma_f32_16x16x32_bf16 v[108:111], v[244:247], v[4:7], v[108:111]
	ds_read_b128 v[244:247], v178 offset:17536
	s_waitcnt lgkmcnt(3)
	v_mfma_f32_16x16x32_bf16 v[56:59], v[250:253], v[4:7], v[56:59]
	ds_read_b128 v[250:253], v178 offset:26240
	s_waitcnt lgkmcnt(3)
	v_mfma_f32_16x16x32_bf16 v[60:63], v[116:119], v[8:11], v[60:63]
	ds_read_b128 v[116:119], v178 offset:192
	s_waitcnt lgkmcnt(3)
	v_mfma_f32_16x16x32_bf16 v[104:107], v[120:123], v[8:11], v[104:107]
	ds_read_b128 v[120:123], v178 offset:8896
	s_waitcnt lgkmcnt(3)
	v_mfma_f32_16x16x32_bf16 v[108:111], v[244:247], v[8:11], v[108:111]
	ds_read_b128 v[244:247], v178 offset:17600
	s_waitcnt lgkmcnt(3)
	v_mfma_f32_16x16x32_bf16 v[56:59], v[250:253], v[8:11], v[56:59]
	ds_read_b128 v[250:253], v178 offset:26304
	s_waitcnt lgkmcnt(3)
	v_mfma_f32_16x16x32_bf16 v[60:63], v[116:119], v[12:15], v[60:63]
	ds_read_b128 v[116:119], v178 offset:256
	s_waitcnt lgkmcnt(3)
	v_mfma_f32_16x16x32_bf16 v[104:107], v[120:123], v[12:15], v[104:107]
	ds_read_b128 v[120:123], v178 offset:8960
	s_waitcnt lgkmcnt(3)
	v_mfma_f32_16x16x32_bf16 v[108:111], v[244:247], v[12:15], v[108:111]
	ds_read_b128 v[244:247], v178 offset:17664
	s_waitcnt lgkmcnt(3)
	v_mfma_f32_16x16x32_bf16 v[56:59], v[250:253], v[12:15], v[56:59]
	ds_read_b128 v[250:253], v178 offset:26368
	s_waitcnt lgkmcnt(3)
	v_mfma_f32_16x16x32_bf16 v[60:63], v[116:119], v[16:19], v[60:63]
	ds_read_b128 v[116:119], v178 offset:320
	s_waitcnt lgkmcnt(3)
	v_mfma_f32_16x16x32_bf16 v[104:107], v[120:123], v[16:19], v[104:107]
	ds_read_b128 v[120:123], v178 offset:9024
	s_waitcnt lgkmcnt(3)
	v_mfma_f32_16x16x32_bf16 v[108:111], v[244:247], v[16:19], v[108:111]
	ds_read_b128 v[244:247], v178 offset:17728
	s_waitcnt lgkmcnt(3)
	v_mfma_f32_16x16x32_bf16 v[56:59], v[250:253], v[16:19], v[56:59]
	ds_read_b128 v[250:253], v178 offset:26432
	s_waitcnt lgkmcnt(3)
	v_mfma_f32_16x16x32_bf16 v[60:63], v[116:119], v[20:23], v[60:63]
	ds_read_b128 v[116:119], v178 offset:384
	s_waitcnt lgkmcnt(3)
	v_mfma_f32_16x16x32_bf16 v[104:107], v[120:123], v[20:23], v[104:107]
	ds_read_b128 v[120:123], v178 offset:9088
	s_waitcnt lgkmcnt(3)
	v_mfma_f32_16x16x32_bf16 v[108:111], v[244:247], v[20:23], v[108:111]
	ds_read_b128 v[244:247], v178 offset:17792
	s_waitcnt lgkmcnt(3)
	v_mfma_f32_16x16x32_bf16 v[56:59], v[250:253], v[20:23], v[56:59]
	ds_read_b128 v[250:253], v178 offset:26496
	s_waitcnt lgkmcnt(3)
	v_mfma_f32_16x16x32_bf16 v[60:63], v[116:119], v[24:27], v[60:63]
	ds_read_b128 v[116:119], v178 offset:448
	s_waitcnt lgkmcnt(3)
	v_mfma_f32_16x16x32_bf16 v[104:107], v[120:123], v[24:27], v[104:107]
	ds_read_b128 v[120:123], v178 offset:9152
	s_waitcnt lgkmcnt(3)
	v_mfma_f32_16x16x32_bf16 v[108:111], v[244:247], v[24:27], v[108:111]
	ds_read_b128 v[244:247], v178 offset:17856
	s_waitcnt lgkmcnt(3)
	v_mfma_f32_16x16x32_bf16 v[56:59], v[250:253], v[24:27], v[56:59]
	ds_read_b128 v[250:253], v178 offset:26560
	s_waitcnt lgkmcnt(3)
	v_mfma_f32_16x16x32_bf16 v[60:63], v[116:119], v[28:31], v[60:63]
	s_waitcnt lgkmcnt(2)
	v_mfma_f32_16x16x32_bf16 v[104:107], v[120:123], v[28:31], v[104:107]
	s_waitcnt lgkmcnt(1)
	v_mfma_f32_16x16x32_bf16 v[108:111], v[244:247], v[28:31], v[108:111]
	s_waitcnt lgkmcnt(0)
	v_mfma_f32_16x16x32_bf16 v[56:59], v[250:253], v[28:31], v[56:59]
	s_mov_b64 s[10:11], -1
	s_cmp_ge_i32 s58, s17
	s_cbranch_scc0 .LBB0_1103
	s_cmp_gt_i32 s58, s17
	s_cbranch_scc1 .LBB0_1100
	v_add_u32_e32 v242, s16, v237
	v_sub_u32_e32 v116, 0, v242
	v_max_i32_e32 v116, v242, v116
	v_cvt_f32_u32_e32 v116, v116
	v_cmp_gt_i32_e32 vcc, 0, v242
	v_add_u32_e32 v118, -1, v242
	v_sub_u32_e32 v119, 2, v242
	v_cndmask_b32_e32 v117, v159, v235, vcc
	v_mul_f32_e32 v116, v117, v116
	v_sub_u32_e32 v117, 1, v242
	v_max_i32_e32 v117, v118, v117
	v_cvt_f32_u32_e32 v117, v117
	v_cmp_gt_i32_e32 vcc, 0, v118
	v_exp_f32_e32 v116, v116
	v_sub_u32_e32 v178, 35, v242
	v_cndmask_b32_e32 v118, v159, v235, vcc
	v_mul_f32_e32 v117, v118, v117
	v_exp_f32_e32 v117, v117
	v_add_u32_e32 v118, -2, v242
	v_max_i32_e32 v119, v118, v119
	v_cmp_gt_i32_e32 vcc, 0, v118
	v_pk_mul_f32 v[120:121], v[116:117], v[60:61]
	v_add_u32_e32 v117, -3, v242
	v_sub_u32_e32 v118, 3, v242
	v_max_i32_e32 v118, v117, v118
	v_cvt_f32_u32_e32 v119, v119
	v_cvt_f32_u32_e32 v118, v118
	v_cndmask_b32_e32 v116, v159, v235, vcc
	v_cmp_gt_i32_e32 vcc, 0, v117
	v_mul_f32_e32 v116, v116, v119
	v_exp_f32_e32 v116, v116
	v_cndmask_b32_e32 v117, v159, v235, vcc
	v_mul_f32_e32 v117, v117, v118
	v_exp_f32_e32 v117, v117
	v_add_u32_e32 v118, -16, v242
	v_sub_u32_e32 v119, 16, v242
	v_max_i32_e32 v119, v118, v119
	v_pk_mul_f32 v[122:123], v[116:117], v[62:63]
	v_cmp_gt_i32_e32 vcc, 0, v118
	v_subrev_u32_e32 v117, 17, v242
	v_sub_u32_e32 v118, 17, v242
	v_max_i32_e32 v118, v117, v118
	v_cvt_f32_u32_e32 v119, v119
	v_cvt_f32_u32_e32 v118, v118
	v_cndmask_b32_e32 v116, v159, v235, vcc
	v_cmp_gt_i32_e32 vcc, 0, v117
	v_mul_f32_e32 v116, v116, v119
	v_exp_f32_e32 v116, v116
	v_cndmask_b32_e32 v117, v159, v235, vcc
	v_mul_f32_e32 v117, v117, v118
	v_exp_f32_e32 v117, v117
	v_subrev_u32_e32 v118, 18, v242
	v_sub_u32_e32 v119, 18, v242
	v_max_i32_e32 v119, v118, v119
	v_pk_mul_f32 v[180:181], v[116:117], v[104:105]
	v_cmp_gt_i32_e32 vcc, 0, v118
	v_subrev_u32_e32 v117, 19, v242
	v_sub_u32_e32 v118, 19, v242
	v_max_i32_e32 v118, v117, v118
	v_cvt_f32_u32_e32 v119, v119
	v_cvt_f32_u32_e32 v118, v118
	v_cndmask_b32_e32 v116, v159, v235, vcc
	v_cmp_gt_i32_e32 vcc, 0, v117
	v_mul_f32_e32 v116, v116, v119
	v_exp_f32_e32 v116, v116
	v_cndmask_b32_e32 v117, v159, v235, vcc
	v_mul_f32_e32 v117, v117, v118
	v_exp_f32_e32 v117, v117
	v_subrev_u32_e32 v118, 32, v242
	v_sub_u32_e32 v119, 32, v242
	v_max_i32_e32 v119, v118, v119
	v_pk_mul_f32 v[182:183], v[116:117], v[106:107]
	v_cmp_gt_i32_e32 vcc, 0, v118
	v_subrev_u32_e32 v117, 33, v242
	v_sub_u32_e32 v118, 33, v242
	v_max_i32_e32 v118, v117, v118
	v_cvt_f32_u32_e32 v119, v119
	v_cvt_f32_u32_e32 v118, v118
	v_cndmask_b32_e32 v116, v159, v235, vcc
	v_cmp_gt_i32_e32 vcc, 0, v117
	v_mul_f32_e32 v116, v116, v119
	v_sub_u32_e32 v119, 34, v242
	v_cndmask_b32_e32 v117, v159, v235, vcc
	v_mul_f32_e32 v117, v117, v118
	v_subrev_u32_e32 v118, 34, v242
	v_max_i32_e32 v119, v118, v119
	v_cvt_f32_u32_e32 v119, v119
	v_cmp_gt_i32_e32 vcc, 0, v118
	v_sub_u32_e32 v179, 48, v242
	v_sub_u32_e32 v243, 49, v242
	v_cndmask_b32_e32 v118, v159, v235, vcc
	v_mul_f32_e32 v118, v118, v119
	v_subrev_u32_e32 v119, 35, v242
	v_max_i32_e32 v178, v119, v178
	v_cvt_f32_u32_e32 v178, v178
	v_cmp_gt_i32_e32 vcc, 0, v119
	v_sub_u32_e32 v244, 50, v242
	v_exp_f32_e32 v116, v116
	v_cndmask_b32_e32 v119, v159, v235, vcc
	v_mul_f32_e32 v119, v119, v178
	v_subrev_u32_e32 v178, 48, v242
	v_max_i32_e32 v179, v178, v179
	v_cvt_f32_u32_e32 v179, v179
	v_cmp_gt_i32_e32 vcc, 0, v178
	v_exp_f32_e32 v117, v117
	v_exp_f32_e32 v118, v118
	v_cndmask_b32_e32 v178, v159, v235, vcc
	v_mul_f32_e32 v178, v178, v179
	v_subrev_u32_e32 v179, 49, v242
	v_max_i32_e32 v243, v179, v243
	v_cvt_f32_u32_e32 v243, v243
	v_cmp_gt_i32_e32 vcc, 0, v179
	v_exp_f32_e32 v119, v119
	v_exp_f32_e32 v178, v178
	v_cndmask_b32_e32 v179, v159, v235, vcc
	v_mul_f32_e32 v179, v179, v243
	v_subrev_u32_e32 v243, 50, v242
	v_max_i32_e32 v244, v243, v244
	v_cvt_f32_u32_e32 v244, v244
	v_cmp_gt_i32_e32 vcc, 0, v243
	v_exp_f32_e32 v179, v179
	v_pk_mul_f32 v[116:117], v[116:117], v[108:109]
	v_cndmask_b32_e32 v243, v159, v235, vcc
	v_mul_f32_e32 v243, v243, v244
	v_subrev_u32_e32 v244, 51, v242
	v_sub_u32_e32 v242, 51, v242
	v_max_i32_e32 v242, v244, v242
	v_cvt_f32_u32_e32 v242, v242
	v_cmp_gt_i32_e32 vcc, 0, v244
	v_exp_f32_e32 v245, v243
	v_pk_mul_f32 v[118:119], v[118:119], v[110:111]
	v_cndmask_b32_e32 v243, v159, v235, vcc
	v_mul_f32_e32 v242, v243, v242
	v_exp_f32_e32 v243, v242
	v_pk_mul_f32 v[178:179], v[178:179], v[56:57]
	v_mul_f32_e32 v242, v245, v58
	s_mov_b64 s[10:11], 0
